# v73 = v72 + four redundant s_nop 1 paddings removed from the past PV stretch (hazard tables re-checked: cvt_pk to MFMA distance stays at 2 or more)
# baseline (speedup 1.0000x reference)
.LBB0_259:
	ds_read_b128 v[72:75], v116 offset:64
	ds_read_b128 v[100:103], v116 offset:2368
	v_mov_b32_e32 v163, v164
	v_add_u32_e32 v164, s0, v121
	s_waitcnt lgkmcnt(2)
	v_mfma_f32_16x16x32_bf16 v[198:201], v[234:237], v[40:43], 0
	v_mov_b32_e32 v165, v166
	v_add_u32_e32 v166, 0x2000, v164
	v_add_u32_e32 v167, 0x4000, v164
	v_mfma_f32_16x16x32_bf16 v[104:107], v[234:237], v[36:39], 0
	ds_read_b128 v[80:83], v116 offset:4608
	ds_read_b128 v[76:79], v116 offset:4672
	s_addk_i32 s0, 0x80
	s_cmpk_eq_i32 s0, 0x200
	v_mfma_f32_16x16x32_bf16 v[68:71], v[238:241], v[40:43], 0
	v_mfma_f32_16x16x32_bf16 v[64:67], v[238:241], v[36:39], 0
	s_waitcnt lgkmcnt(1)
	v_mfma_f32_16x16x32_bf16 v[92:95], v[80:83], v[40:43], 0
	v_mfma_f32_16x16x32_bf16 v[84:87], v[80:83], v[36:39], 0
	ds_read_b128 v[88:91], v116 offset:6912
	ds_read_b128 v[80:83], v116 offset:6976
	v_add_u32_e32 v116, 0x2400, v116
	s_waitcnt lgkmcnt(1)
	v_mfma_f32_16x16x32_bf16 v[96:99], v[88:91], v[40:43], 0
	v_mfma_f32_16x16x32_bf16 v[88:91], v[88:91], v[36:39], 0
	v_mfma_f32_16x16x32_bf16 v[68:71], v[72:75], v[44:47], v[68:71]
	v_mfma_f32_16x16x32_bf16 v[72:75], v[72:75], v[32:35], v[64:67]
	v_mfma_f32_16x16x32_bf16 v[64:67], v[100:103], v[44:47], v[198:201]
	v_mfma_f32_16x16x32_bf16 v[100:103], v[100:103], v[32:35], v[104:107]
	s_nop 2
	ds_read2_b64 v[104:107], v164 offset1:4
	ds_read2_b64 v[198:201], v164 offset0:8 offset1:12
	v_add_u32_e32 v164, 0x6000, v164
	v_mfma_f32_16x16x32_bf16 v[92:95], v[76:79], v[44:47], v[92:95]
	v_mfma_f32_16x16x32_bf16 v[76:79], v[76:79], v[32:35], v[84:87]
	s_nop 2
	ds_read2_b64 v[84:87], v166 offset0:32 offset1:36
	ds_read2_b64 v[202:205], v166 offset0:40 offset1:44
	ds_read2_b64 v[206:209], v167 offset0:64 offset1:68
	ds_read2_b64 v[210:213], v167 offset0:72 offset1:76
	ds_read2_b64 v[214:217], v164 offset0:96 offset1:100
	ds_read2_b64 v[218:221], v164 offset0:104 offset1:108
	s_waitcnt lgkmcnt(8)
	v_mfma_f32_16x16x32_bf16 v[96:99], v[80:83], v[44:47], v[96:99]
	v_mfma_f32_16x16x32_bf16 v[80:83], v[80:83], v[32:35], v[88:91]
	s_nop 2
	v_max3_f32 v88, v68, s4, v69
	v_max3_f32 v89, v72, s4, v73
	v_max3_f32 v88, v88, v70, v71
	v_max3_f32 v89, v89, v74, v75
	v_max3_f32 v88, v88, v64, v65
	v_max3_f32 v89, v89, v100, v101
	v_max3_f32 v88, v88, v66, v67
	v_max3_f32 v89, v89, v102, v103
	v_max3_f32 v88, v88, v92, v93
	v_max3_f32 v89, v89, v76, v77
	v_max3_f32 v88, v88, v94, v95
	v_max3_f32 v89, v89, v78, v79
	v_max3_f32 v88, v88, v96, v97
	v_max3_f32 v89, v89, v80, v81
	v_max3_f32 v88, v88, v98, v99
	v_max3_f32 v89, v89, v82, v83
	v_mov_b32_e32 v90, v88
	v_mov_b32_e32 v91, v89
	s_nop 0
	v_permlane16_swap_b32_e32 v90, v88
	v_permlane16_swap_b32_e32 v91, v89
	v_max_f32_e32 v88, v88, v90
	v_max_f32_e32 v89, v89, v91
	v_mov_b32_e32 v90, v88
	v_mov_b32_e32 v91, v89
	s_nop 0
	v_permlane32_swap_b32_e32 v90, v88
	v_permlane32_swap_b32_e32 v91, v89
	v_max3_f32 v164, v163, v89, v91
	v_max3_f32 v166, v165, v88, v90
	v_sub_f32_e32 v89, v163, v164
	v_sub_f32_e32 v88, v165, v166
	v_sub_f32_e32 v90, 0, v166
	v_sub_f32_e32 v178, 0, v164
	v_pk_add_f32 v[68:69], v[68:69], v[90:91] op_sel_hi:[1,0]
	v_pk_add_f32 v[70:71], v[70:71], v[90:91] op_sel_hi:[1,0]
	v_pk_add_f32 v[72:73], v[72:73], v[178:179] op_sel_hi:[1,0]
	v_pk_add_f32 v[74:75], v[74:75], v[178:179] op_sel_hi:[1,0]
	v_exp_f32_e32 v88, v88
	v_exp_f32_e32 v89, v89
	v_pk_add_f32 v[64:65], v[64:65], v[90:91] op_sel_hi:[1,0]
	v_pk_add_f32 v[66:67], v[66:67], v[90:91] op_sel_hi:[1,0]
	v_mov_b32_e32 v186, v89
	v_exp_f32_e32 v68, v68
	v_exp_f32_e32 v69, v69
	v_exp_f32_e32 v70, v70
	v_exp_f32_e32 v71, v71
	v_pk_add_f32 v[100:101], v[100:101], v[178:179] op_sel_hi:[1,0]
	v_pk_add_f32 v[102:103], v[102:103], v[178:179] op_sel_hi:[1,0]
	v_exp_f32_e32 v72, v72
	v_exp_f32_e32 v73, v73
	v_exp_f32_e32 v74, v74
	v_exp_f32_e32 v75, v75
	v_pk_mul_f32 v[60:61], v[60:61], v[88:89] op_sel_hi:[1,0]
	v_pk_mul_f32 v[62:63], v[62:63], v[88:89] op_sel_hi:[1,0]
	v_exp_f32_e32 v64, v64
	v_exp_f32_e32 v65, v65
	v_exp_f32_e32 v66, v66
	v_exp_f32_e32 v67, v67
	v_pk_mul_f32 v[56:57], v[56:57], v[88:89] op_sel_hi:[1,0]
	v_pk_mul_f32 v[58:59], v[58:59], v[88:89] op_sel_hi:[1,0]
	v_exp_f32_e32 v100, v100
	v_exp_f32_e32 v101, v101
	v_exp_f32_e32 v102, v102
	v_exp_f32_e32 v103, v103
	v_cvt_pk_bf16_f32 v222, v68, v69
	v_cvt_pk_bf16_f32 v223, v70, v71
	v_cvt_pk_bf16_f32 v224, v64, v65
	v_cvt_pk_bf16_f32 v225, v66, v67
	v_mul_f32_e32 v28, v28, v186
	v_mul_f32_e32 v29, v29, v186
	v_mul_f32_e32 v30, v30, v186
	v_mul_f32_e32 v31, v31, v186
	s_waitcnt lgkmcnt(7)
	v_mfma_f32_16x16x32_bf16 v[60:63], v[104:107], v[222:225], v[60:63]
	v_cvt_pk_bf16_f32 v226, v72, v73
	v_cvt_pk_bf16_f32 v227, v74, v75
	s_waitcnt lgkmcnt(5)
	v_mfma_f32_16x16x32_bf16 v[56:59], v[84:87], v[222:225], v[56:59]
	v_cvt_pk_bf16_f32 v228, v100, v101
	v_cvt_pk_bf16_f32 v229, v102, v103
	v_mul_f32_e32 v24, v24, v186
	v_mul_f32_e32 v25, v25, v186
	v_mul_f32_e32 v26, v26, v186
	v_mul_f32_e32 v27, v27, v186
	v_mfma_f32_16x16x32_bf16 v[28:31], v[104:107], v[226:229], v[28:31]
	v_add_f32_e32 v92, v92, v90
	v_add_f32_e32 v93, v93, v90
	v_add_f32_e32 v94, v94, v90
	v_add_f32_e32 v95, v95, v90
	v_mul_f32_e32 v52, v52, v88
	v_mul_f32_e32 v53, v53, v88
	v_mul_f32_e32 v54, v54, v88
	v_mul_f32_e32 v55, v55, v88
	v_mfma_f32_16x16x32_bf16 v[24:27], v[84:87], v[226:229], v[24:27]
	v_add_f32_e32 v96, v96, v90
	v_add_f32_e32 v97, v97, v90
	v_add_f32_e32 v98, v98, v90
	v_add_f32_e32 v99, v99, v90
	v_mul_f32_e32 v48, v48, v88
	v_mul_f32_e32 v49, v49, v88
	v_mul_f32_e32 v50, v50, v88
	v_mul_f32_e32 v51, v51, v88
	s_waitcnt lgkmcnt(3)
	v_mfma_f32_16x16x32_bf16 v[52:55], v[206:209], v[222:225], v[52:55]
	v_exp_f32_e32 v92, v92
	v_exp_f32_e32 v93, v93
	v_exp_f32_e32 v94, v94
	v_exp_f32_e32 v95, v95
	s_waitcnt lgkmcnt(1)
	v_mfma_f32_16x16x32_bf16 v[48:51], v[214:217], v[222:225], v[48:51]
	v_exp_f32_e32 v96, v96
	v_exp_f32_e32 v97, v97
	v_exp_f32_e32 v98, v98
	v_exp_f32_e32 v99, v99
	v_add_f32_e32 v76, v76, v178
	v_add_f32_e32 v77, v77, v178
	v_add_f32_e32 v78, v78, v178
	v_add_f32_e32 v79, v79, v178
	v_add_f32_e32 v80, v80, v178
	v_add_f32_e32 v81, v81, v178
	v_add_f32_e32 v82, v82, v178
	v_add_f32_e32 v83, v83, v178
	v_cvt_pk_bf16_f32 v222, v92, v93
	v_cvt_pk_bf16_f32 v223, v94, v95
	v_cvt_pk_bf16_f32 v224, v96, v97
	v_cvt_pk_bf16_f32 v225, v98, v99
	v_exp_f32_e32 v76, v76
	v_exp_f32_e32 v77, v77
	v_mfma_f32_16x16x32_bf16 v[60:63], v[198:201], v[222:225], v[60:63]
	v_exp_f32_e32 v78, v78
	v_exp_f32_e32 v79, v79
	v_mfma_f32_16x16x32_bf16 v[56:59], v[202:205], v[222:225], v[56:59]
	v_exp_f32_e32 v80, v80
	v_exp_f32_e32 v81, v81
	v_mfma_f32_16x16x32_bf16 v[52:55], v[210:213], v[222:225], v[52:55]
	v_exp_f32_e32 v82, v82
	v_exp_f32_e32 v83, v83
	s_waitcnt lgkmcnt(0)
	v_mfma_f32_16x16x32_bf16 v[48:51], v[218:221], v[222:225], v[48:51]
	ds_read_b128 v[234:237], v116 offset:2304
	ds_read_b128 v[238:241], v116
	v_mul_f32_e32 v20, v20, v186
	v_mul_f32_e32 v21, v21, v186
	v_mul_f32_e32 v22, v22, v186
	v_mul_f32_e32 v23, v23, v186
	v_mul_f32_e32 v16, v16, v186
	v_mul_f32_e32 v17, v17, v186
	v_mul_f32_e32 v18, v18, v186
	v_mul_f32_e32 v19, v19, v186
	v_mfma_f32_16x16x32_bf16 v[20:23], v[206:209], v[226:229], v[20:23]
	v_add_f32_e32 v90, v68, v70
	v_add_f32_e32 v91, v69, v71
	v_add_f32_e32 v178, v72, v74
	v_add_f32_e32 v179, v73, v75
	v_mfma_f32_16x16x32_bf16 v[16:19], v[214:217], v[226:229], v[16:19]
	v_cvt_pk_bf16_f32 v226, v76, v77
	v_cvt_pk_bf16_f32 v227, v78, v79
	v_cvt_pk_bf16_f32 v228, v80, v81
	v_cvt_pk_bf16_f32 v229, v82, v83
	v_add_f32_e32 v90, v90, v64
	v_add_f32_e32 v91, v91, v65
	v_add_f32_e32 v178, v178, v100
	v_add_f32_e32 v179, v179, v101
	v_mfma_f32_16x16x32_bf16 v[28:31], v[198:201], v[226:229], v[28:31]
	v_add_f32_e32 v90, v90, v66
	v_add_f32_e32 v91, v91, v67
	v_add_f32_e32 v178, v178, v102
	v_add_f32_e32 v179, v179, v103
	v_mfma_f32_16x16x32_bf16 v[24:27], v[202:205], v[226:229], v[24:27]
	v_add_f32_e32 v90, v90, v92
	v_add_f32_e32 v91, v91, v93
	v_add_f32_e32 v178, v178, v76
	v_add_f32_e32 v179, v179, v77
	v_mfma_f32_16x16x32_bf16 v[20:23], v[210:213], v[226:229], v[20:23]
	v_add_f32_e32 v90, v90, v94
	v_add_f32_e32 v91, v91, v95
	v_add_f32_e32 v178, v178, v78
	v_add_f32_e32 v179, v179, v79
	v_mfma_f32_16x16x32_bf16 v[16:19], v[218:221], v[226:229], v[16:19]
	v_add_f32_e32 v90, v90, v96
	v_add_f32_e32 v91, v91, v97
	v_add_f32_e32 v178, v178, v80
	v_add_f32_e32 v179, v179, v81
	v_add_f32_e32 v90, v90, v98
	v_add_f32_e32 v91, v91, v99
	v_add_f32_e32 v178, v178, v82
	v_add_f32_e32 v179, v179, v83
	v_add_f32_e32 v64, v90, v91
	v_add_f32_e32 v65, v178, v179
	v_fma_f32 v158, v158, v88, v64
	v_fma_f32 v159, v159, v89, v65
	s_cmpk_lg_i32 s0, 0x80
	s_cbranch_scc1 .Lpast_qskip
	s_cmp_lg_u64 s[22:23], 0
	s_cbranch_scc1 .Lpast_qskip
	v_mov_b32_e32 v233, 0
	s_waitcnt vmcnt(1)
	v_and_b32_e32 v137, 0xfff, v141
	v_lshlrev_b32_e32 v232, 7, v137
	v_lshl_add_u64 v[4:5], v[156:157], 0, v[232:233]
	global_load_dwordx4 v[0:3], v[4:5], off
	s_nop 0
	global_load_dwordx4 v[4:7], v[4:5], off offset:64
	s_waitcnt vmcnt(2)
	v_and_b32_e32 v139, 0xfff, v149
	v_lshlrev_b32_e32 v232, 7, v139
	v_lshl_add_u64 v[12:13], v[156:157], 0, v[232:233]
	global_load_dwordx4 v[8:11], v[12:13], off
	s_nop 0
	global_load_dwordx4 v[12:15], v[12:13], off offset:64
